# NORM row loop: all eight modulation-vector loads issued with the row loads (one wait) instead of four serialized L2 round trips per row
# speedup vs baseline: 1.0028x; 1.0028x over previous
; __device__ __forceinline__ unsigned pk2(float lo, float hi) { f32x2v v = {lo, hi}; bf16x2v b = __builtin_convertvector(v, bf16x2v); return __builtin_bit_cast(unsigned, b); }
; __device__ __forceinline__ void norm_phase(const float* xs, const float* cs, const float* g, const float* modl, int which, bf16_t* A1, int nrows, int tid) {
;     ...
;     for (int row = blockIdx.x * 8 + wave; row < nrows; row += gridDim.x * 8) {
;         const float* src = row < MX ? xs + (size_t)row * DM : cs + (size_t)(row - MX) * DM;
;         const int bp = row < MX ? (row >> 12) : 8;
;         const float* sh = modl + (size_t)bp * 6144 + which * 3 * 1024; const float* scl = sh + 1024;
;         f32x4 v[4]; float ss = 0.f;
; #pragma unroll
;         for (int j = 0; j < 4; ++j) { v[j] = __builtin_nontemporal_load((const f32x4*)(src + 4 * lane + 256 * j)); ss += (v[j][0] * v[j][0] + v[j][1] * v[j][1]) + (v[j][2] * v[j][2] + v[j][3] * v[j][3]); }
;         const float r = rsqrtf(wave_sum(ss) * (1.0f / 1024.0f) + 1e-6f);
; #pragma unroll
;         for (int j = 0; j < 4; ++j) {
;             const f32x4 s1 = *(const f32x4*)(scl + 4 * lane + 256 * j), s0 = *(const f32x4*)(sh + 4 * lane + 256 * j);
;             f32x4 y = v[j] * r * gvv[j]; y = y * (s1 + 1.0f) + s0;
;             *(u32x2*)(A1 + (size_t)row * DM + 4 * lane + 256 * j) = (u32x2){pk2(y[0], y[1]), pk2(y[2], y[3])};
;         }
.LBB0_147:
	s_or_b64 exec, exec, s[6:7]
	v_lshl_add_u64 v[22:23], v[22:23], 0, v[20:21]
	global_load_dwordx4 v[30:33], v[22:23], off nt
	global_load_dwordx4 v[34:37], v[22:23], off offset:1024 nt
	global_load_dwordx4 v[38:41], v[22:23], off offset:3072 nt
	global_load_dwordx4 v[42:45], v[22:23], off offset:2048 nt
	v_min_i32_e32 v22, 0x8000, v16
	v_ashrrev_i32_e32 v22, 12, v22
	v_readlane_b32 s6, v253, 41
	v_mul_hi_i32_i24_e32 v23, 0x6000, v22
	v_mul_i32_i24_e32 v22, 0x6000, v22
	v_readlane_b32 s7, v253, 42
	s_nop 1
	v_lshl_add_u64 v[22:23], s[6:7], 0, v[22:23]
	v_lshl_add_u64 v[22:23], v[22:23], 0, v[20:21]
	s_mov_b64 s[6:7], 0x1000
	v_lshl_add_u64 v[56:57], v[22:23], 0, s[6:7]
	global_load_dwordx4 v[72:75], v[56:57], off
	global_load_dwordx4 v[88:91], v[22:23], off
	global_load_dwordx4 v[76:79], v[56:57], off offset:1024
	global_load_dwordx4 v[92:95], v[22:23], off offset:1024
	global_load_dwordx4 v[80:83], v[56:57], off offset:2048
	global_load_dwordx4 v[96:99], v[22:23], off offset:2048
	global_load_dwordx4 v[84:87], v[56:57], off offset:3072
	global_load_dwordx4 v[100:103], v[22:23], off offset:3072
	s_waitcnt vmcnt(8)
	v_pk_mul_f32 v[54:55], v[32:33], v[32:33]
	v_pk_mul_f32 v[56:57], v[30:31], v[30:31]
	s_nop 0
	s_nop 0
	v_pk_mul_f32 v[58:59], v[36:37], v[36:37]
	v_pk_mul_f32 v[60:61], v[34:35], v[34:35]
	v_pk_mov_b32 v[66:67], v[56:57], v[54:55] op_sel:[1,0]
	v_mov_b32_e32 v57, v55
	v_pk_mov_b32 v[54:55], v[60:61], v[58:59] op_sel:[1,0]
	v_mov_b32_e32 v61, v59
	v_mul_f32_e32 v65, v38, v38
	v_mul_f32_e32 v62, v43, v43
	v_mul_f32_e32 v64, v45, v45
	v_pk_add_f32 v[56:57], v[66:67], v[56:57]
	v_pk_add_f32 v[54:55], v[54:55], v[60:61]
	v_mul_f32_e32 v68, v39, v39
	v_mul_f32_e32 v69, v40, v40
	v_mul_f32_e32 v70, v41, v41
	v_pk_fma_f32 v[58:59], v[42:43], v[42:43], v[62:63] op_sel_hi:[1,1,0]
	v_pk_fma_f32 v[62:63], v[44:45], v[44:45], v[64:65] op_sel_hi:[1,1,0]
	v_pk_add_f32 v[56:57], v[56:57], v[56:57] op_sel:[0,1] op_sel_hi:[1,0]
	v_pk_add_f32 v[54:55], v[54:55], v[54:55] op_sel:[0,1] op_sel_hi:[1,0]
	v_mov_b32_e32 v59, v69
	v_mov_b32_e32 v63, v70
	v_mov_b32_e32 v57, v65
	v_mov_b32_e32 v55, v68
	v_pk_add_f32 v[58:59], v[58:59], v[62:63]
	v_pk_add_f32 v[54:55], v[56:57], v[54:55]
	v_pk_add_f32 v[54:55], v[54:55], v[58:59]
	v_add_f32_e32 v54, v54, v55
	ds_bpermute_b32 v55, v24, v54
	s_waitcnt lgkmcnt(0)
	v_add_f32_e32 v54, v54, v55
	ds_bpermute_b32 v55, v25, v54
	s_waitcnt lgkmcnt(0)
	v_add_f32_e32 v54, v54, v55
	ds_bpermute_b32 v55, v26, v54
	s_waitcnt lgkmcnt(0)
	v_add_f32_e32 v54, v54, v55
	ds_bpermute_b32 v55, v27, v54
	s_waitcnt lgkmcnt(0)
	v_add_f32_e32 v54, v54, v55
	ds_bpermute_b32 v55, v28, v54
	s_waitcnt lgkmcnt(0)
	v_add_f32_e32 v56, v54, v55
	ds_bpermute_b32 v57, v29, v56
	v_lshlrev_b64 v[54:55], 11, v[16:17]
	v_lshl_add_u64 v[54:55], v[18:19], 0, v[54:55]
	v_add_u32_e32 v16, s40, v16
	s_waitcnt lgkmcnt(0)
	v_add_f32_e32 v17, v56, v57
	v_fmamk_f32 v17, v17, 0x3a800000, v221
	v_mul_f32_e32 v56, 0x4b800000, v17
	v_cmp_gt_f32_e32 vcc, s16, v17
	s_nop 1
	v_cndmask_b32_e32 v17, v17, v56, vcc
	v_rsq_f32_e32 v17, v17
	v_mul_f32_e32 v58, 0x45800000, v17
	v_cndmask_b32_e32 v58, v17, v58, vcc
	s_mov_b32 s6, 0x87ff
	v_cmp_lt_i32_e32 vcc, s6, v16
	s_or_b64 s[4:5], vcc, s[4:5]
	s_waitcnt vmcnt(0)
	v_pk_mul_f32 v[32:33], v[32:33], v[58:59] op_sel_hi:[1,0]
	v_pk_mul_f32 v[30:31], v[30:31], v[58:59] op_sel_hi:[1,0]
	v_pk_mul_f32 v[32:33], v[2:3], v[32:33]
	v_pk_mul_f32 v[30:31], v[0:1], v[30:31]
	v_pk_add_f32 v[74:75], v[74:75], 1.0 op_sel_hi:[1,0]
	v_pk_add_f32 v[72:73], v[72:73], 1.0 op_sel_hi:[1,0]
	v_pk_fma_f32 v[32:33], v[74:75], v[32:33], v[90:91]
	v_pk_fma_f32 v[30:31], v[72:73], v[30:31], v[88:89]
	s_nop 0
	v_cvt_pk_bf16_f32 v30, v30, v31
	v_cvt_pk_bf16_f32 v31, v32, v33
	global_store_dwordx2 v[54:55], v[30:31], off
	v_pk_mul_f32 v[36:37], v[36:37], v[58:59] op_sel_hi:[1,0]
	v_pk_mul_f32 v[34:35], v[34:35], v[58:59] op_sel_hi:[1,0]
	v_pk_mul_f32 v[36:37], v[6:7], v[36:37]
	v_pk_mul_f32 v[34:35], v[4:5], v[34:35]
	v_pk_add_f32 v[78:79], v[78:79], 1.0 op_sel_hi:[1,0]
	v_pk_add_f32 v[76:77], v[76:77], 1.0 op_sel_hi:[1,0]
	v_pk_fma_f32 v[36:37], v[78:79], v[36:37], v[94:95]
	v_pk_fma_f32 v[34:35], v[76:77], v[34:35], v[92:93]
	s_nop 0
	v_cvt_pk_bf16_f32 v34, v34, v35
	v_cvt_pk_bf16_f32 v35, v36, v37
	global_store_dwordx2 v[54:55], v[34:35], off offset:512
	v_pk_mul_f32 v[44:45], v[44:45], v[58:59] op_sel_hi:[1,0]
	v_pk_mul_f32 v[42:43], v[42:43], v[58:59] op_sel_hi:[1,0]
	v_pk_mul_f32 v[44:45], v[10:11], v[44:45]
	v_pk_mul_f32 v[42:43], v[8:9], v[42:43]
	v_pk_add_f32 v[82:83], v[82:83], 1.0 op_sel_hi:[1,0]
	v_pk_add_f32 v[80:81], v[80:81], 1.0 op_sel_hi:[1,0]
	v_pk_fma_f32 v[44:45], v[82:83], v[44:45], v[98:99]
	v_pk_fma_f32 v[42:43], v[80:81], v[42:43], v[96:97]
	s_nop 0
	v_cvt_pk_bf16_f32 v42, v42, v43
	v_cvt_pk_bf16_f32 v43, v44, v45
	global_store_dwordx2 v[54:55], v[42:43], off offset:1024
	v_pk_mul_f32 v[40:41], v[40:41], v[58:59] op_sel_hi:[1,0]
	v_pk_mul_f32 v[38:39], v[38:39], v[58:59] op_sel_hi:[1,0]
	v_pk_mul_f32 v[40:41], v[14:15], v[40:41]
	v_pk_mul_f32 v[38:39], v[12:13], v[38:39]
	v_pk_add_f32 v[86:87], v[86:87], 1.0 op_sel_hi:[1,0]
	v_pk_add_f32 v[84:85], v[84:85], 1.0 op_sel_hi:[1,0]
	v_pk_fma_f32 v[40:41], v[86:87], v[40:41], v[102:103]
	v_pk_fma_f32 v[38:39], v[84:85], v[38:39], v[100:101]
	s_nop 0
	v_cvt_pk_bf16_f32 v38, v38, v39
	v_cvt_pk_bf16_f32 v39, v40, v41
	global_store_dwordx2 v[54:55], v[38:39], off offset:1536
	s_andn2_b64 exec, exec, s[4:5]
	s_cbranch_execz .LBB0_153
